# batched serialized loads in mod_task loop, ssd_p3 prologue, resid16 ssq; grid-barrier release/acquire waits added
# speedup vs baseline: 1.0774x; 1.0319x over previous
.LBB0_2:
	s_waitcnt lgkmcnt(0)
	buffer_inv sc1
	s_waitcnt vmcnt(0)

.LBB0_179:
	s_andn2_b64 vcc, exec, s[0:1]
	s_cbranch_vccnz .LBB0_209
	s_sub_i32 s0, s20, s19
	s_ashr_i32 s4, s0, 4
	s_lshl_b32 s10, s4, 7
	s_ashr_i32 s11, s10, 31
	s_and_b32 s14, s20, 15
	v_mov_b32_e32 v34, v0
	s_lshl_b64 s[2:3], s[10:11], 9
	v_readlane_b32 s1, v253, 61
	s_add_u32 s1, s1, s2
	v_ashrrev_i32_e32 v220, 6, v34
	v_readlane_b32 s5, v253, 62
	v_and_b32_e32 v219, 15, v34
	s_addc_u32 s5, s5, s3
	s_lshl_b32 s6, s20, 5
	v_lshlrev_b32_e32 v1, 5, v220
	s_and_b32 s8, s6, 0x100
	v_or_b32_e32 v138, v1, v219
	s_add_u32 s6, s1, s8
	v_ashrrev_i32_e32 v139, 31, v138
	v_bfe_u32 v155, v34, 4, 2
	s_addc_u32 s7, s5, 0
	v_readlane_b32 s1, v253, 63
	s_waitcnt vmcnt(0)
	v_lshlrev_b64 v[46:47], 9, v[138:139]
	s_add_u32 s5, s1, s2
	v_readlane_b32 s9, v254, 0
	v_lshl_add_u64 v[48:49], s[6:7], 0, v[46:47]
	v_lshlrev_b32_e32 v46, 4, v155
	s_addc_u32 s15, s9, s3
	v_mov_b32_e32 v50, v46
	v_mov_b32_e32 v51, v131
	v_lshl_add_u64 v[52:53], v[48:49], 0, v[50:51]
	s_movk_i32 s9, 0x2000
	v_add_co_u32_e32 v46, vcc, s9, v52
	s_add_u32 s9, s5, s8
	v_ashrrev_i32_e32 v47, 4, v34
	s_addc_u32 s5, s15, 0
	v_lshlrev_b32_e32 v48, 4, v219
	v_mov_b32_e32 v49, v131
	v_ashrrev_i32_e32 v50, 31, v47
	v_add_u32_e32 v51, 16, v47
	v_add_u32_e32 v54, 32, v47
	v_add_u32_e32 v55, 48, v47
	s_mov_b32 s16, s9
	s_mov_b32 s17, s5
	v_lshl_add_u64 v[56:57], s[16:17], 0, v[48:49]
	v_mov_b32_e32 v48, v47
	v_mov_b32_e32 v49, v50
	v_lshlrev_b64 v[58:59], 9, v[48:49]
	v_ashrrev_i32_e32 v47, 31, v51
	v_ashrrev_i32_e32 v48, 31, v54
	v_ashrrev_i32_e32 v49, 31, v55
	v_addc_co_u32_e32 v50, vcc, 0, v53, vcc
	v_lshl_add_u64 v[60:61], v[56:57], 0, v[58:59]
	v_mov_b32_e32 v58, v51
	v_mov_b32_e32 v59, v47
	v_lshlrev_b64 v[62:63], 9, v[58:59]
	v_mov_b32_e32 v58, v54
	v_mov_b32_e32 v59, v48
	v_lshlrev_b64 v[64:65], 9, v[58:59]
	v_mov_b32_e32 v58, v55
	v_mov_b32_e32 v59, v49
	v_lshlrev_b64 v[66:67], 9, v[58:59]
	global_load_dwordx4 v[68:71], v[52:53], off
	v_mov_b32_e32 v48, v46
	v_mov_b32_e32 v49, v50
	global_load_dwordx4 v[72:75], v[48:49], off
	global_load_dwordx4 v[76:79], v[52:53], off offset:64
	v_mov_b32_e32 v48, v46
	v_mov_b32_e32 v49, v50
	global_load_dwordx4 v[80:83], v[48:49], off offset:64
	global_load_dwordx4 v[84:87], v[52:53], off offset:128
	v_mov_b32_e32 v48, v46
	v_mov_b32_e32 v49, v50
	global_load_dwordx4 v[88:91], v[48:49], off offset:128
	global_load_dwordx4 v[92:95], v[52:53], off offset:192
	v_mov_b32_e32 v48, v46
	v_mov_b32_e32 v49, v50
	global_load_dwordx4 v[52:55], v[48:49], off offset:192
	v_lshl_add_u64 v[46:47], v[56:57], 0, v[62:63]
	v_lshl_add_u64 v[48:49], v[56:57], 0, v[64:65]
	v_lshl_add_u64 v[50:51], v[56:57], 0, v[66:67]
	global_load_dwordx4 v[56:59], v[60:61], off
	s_mov_b32 s5, 0x8000
	s_lshl_b32 s9, s14, 2
	global_load_dwordx4 v[62:65], v[46:47], off
	global_load_dwordx4 v[96:99], v[48:49], off
	global_load_dwordx4 v[46:49], v[50:51], off
	v_add_co_u32_e32 v50, vcc, s5, v60
	s_mov_b32 s5, 0xa000
	s_nop 0
	v_addc_co_u32_e32 v51, vcc, 0, v61, vcc
	global_load_dwordx4 v[100:103], v[50:51], off
	v_add_co_u32_e32 v50, vcc, s5, v60
	s_mov_b32 s5, 0xc000
	s_nop 0
	v_addc_co_u32_e32 v51, vcc, 0, v61, vcc
	global_load_dwordx4 v[104:107], v[50:51], off
	v_add_co_u32_e32 v50, vcc, s5, v60
	s_mov_b32 s5, 0xe000
	s_nop 0
	v_addc_co_u32_e32 v51, vcc, 0, v61, vcc
	global_load_dwordx4 v[108:111], v[50:51], off
	v_add_co_u32_e32 v50, vcc, s5, v60
	v_readlane_b32 s5, v254, 62
	s_nop 0
	v_addc_co_u32_e32 v51, vcc, 0, v61, vcc
	global_load_dwordx4 v[112:115], v[50:51], off
	v_mov_b32_e32 v50, v0
	v_and_b32_e32 v51, 0x7f, v50
	v_or_b32_e32 v60, s10, v51
	v_ashrrev_i32_e32 v51, 31, v60
	v_ashrrev_i32_e32 v61, 3, v50
	v_and_b32_e32 v50, -16, v61
	v_mov_b32_e32 v66, v60
	v_mov_b32_e32 v67, v51
	v_lshlrev_b64 v[116:117], 7, v[66:67]
	v_ashrrev_i32_e32 v51, 31, v50
	v_lshl_add_u64 v[60:61], s[30:31], 0, v[116:117]
	v_lshl_add_u64 v[66:67], v[50:51], 2, v[60:61]
	s_mov_b32 s16, s9
	s_mov_b32 s17, s89
	v_lshl_add_u64 v[60:61], v[66:67], 0, s[16:17]
	global_load_dword v51, v[60:61], off
	v_add_u32_e32 v60, s5, v50
	v_or_b32_e32 v50, s14, v60
	v_ashrrev_i32_e32 v60, 31, v50
	v_mov_b32_e32 v66, v50
	v_mov_b32_e32 v67, v60
	v_lshl_add_u64 v[116:117], v[66:67], 2, s[60:61]
	global_load_dword v50, v[116:117], off
	v_lshlrev_b64 v[2:3], 9, v[138:139]
	s_add_u32 s1, s1, s2
	v_readlane_b32 s2, v254, 0
	v_lshl_add_u64 v[2:3], s[6:7], 0, v[2:3]
	v_lshlrev_b32_e32 v130, 4, v155
	s_addc_u32 s3, s2, s3
	v_lshl_add_u64 v[6:7], v[2:3], 0, v[130:131]
	s_movk_i32 s2, 0x2000
	v_add_co_u32_e32 v8, vcc, s2, v6
	s_add_u32 s2, s1, s8
	v_ashrrev_i32_e32 v144, 4, v34
	s_addc_u32 s3, s3, 0
	v_lshlrev_b32_e32 v34, 4, v219
	v_mov_b32_e32 v35, v131
	v_ashrrev_i32_e32 v145, 31, v144
	v_add_u32_e32 v146, 16, v144
	v_add_u32_e32 v150, 32, v144
	v_add_u32_e32 v148, 48, v144
	v_lshl_add_u64 v[36:37], s[2:3], 0, v[34:35]
	v_lshlrev_b64 v[38:39], 9, v[144:145]
	v_ashrrev_i32_e32 v147, 31, v146
	v_ashrrev_i32_e32 v151, 31, v150
	v_ashrrev_i32_e32 v149, 31, v148
	v_addc_co_u32_e32 v9, vcc, 0, v7, vcc
	v_lshl_add_u64 v[38:39], v[36:37], 0, v[38:39]
	v_lshlrev_b64 v[40:41], 9, v[146:147]
	v_lshlrev_b64 v[42:43], 9, v[150:151]
	v_lshlrev_b64 v[44:45], 9, v[148:149]
	s_movk_i32 s1, 0x110
	s_waitcnt vmcnt(0)
	v_mov_b32_e32 v30, v68
	v_mov_b32_e32 v31, v69
	v_mov_b32_e32 v32, v70
	v_mov_b32_e32 v33, v71
	v_mov_b32_e32 v14, v72
	v_mov_b32_e32 v15, v73
	v_mov_b32_e32 v16, v74
	v_mov_b32_e32 v17, v75
	v_mov_b32_e32 v26, v76
	v_mov_b32_e32 v27, v77
	v_mov_b32_e32 v28, v78
	v_mov_b32_e32 v29, v79
	v_mov_b32_e32 v2, v80
	v_mov_b32_e32 v3, v81
	v_mov_b32_e32 v4, v82
	v_mov_b32_e32 v5, v83
	v_mov_b32_e32 v22, v84
	v_mov_b32_e32 v23, v85
	v_mov_b32_e32 v24, v86
	v_mov_b32_e32 v25, v87
	v_mov_b32_e32 v10, v88
	v_mov_b32_e32 v11, v89
	v_mov_b32_e32 v12, v90
	v_mov_b32_e32 v13, v91
	v_mov_b32_e32 v18, v92
	v_mov_b32_e32 v19, v93
	v_mov_b32_e32 v20, v94
	v_mov_b32_e32 v21, v95
	s_nop 0
	v_mov_b32_e32 v6, v52
	v_mov_b32_e32 v7, v53
	v_mov_b32_e32 v8, v54
	v_mov_b32_e32 v9, v55
	s_barrier
	v_lshl_add_u64 v[40:41], v[36:37], 0, v[40:41]
	v_lshl_add_u64 v[42:43], v[36:37], 0, v[42:43]
	v_lshl_add_u64 v[44:45], v[36:37], 0, v[44:45]
	v_mad_u64_u32 v[142:143], s[6:7], v144, s1, v[34:35]
	s_mov_b32 s1, 0x8000
	s_lshl_b32 s88, s14, 2
	ds_write_b128 v142, v[56:59] offset:34816
	ds_write_b128 v142, v[62:65] offset:39168
	ds_write_b128 v142, v[96:99] offset:43520
	ds_write_b128 v142, v[46:49] offset:47872
	v_add_co_u32_e32 v34, vcc, s1, v38
	s_mov_b32 s1, 0xa000
	s_nop 0
	v_addc_co_u32_e32 v35, vcc, 0, v39, vcc
	ds_write_b128 v142, v[100:103] offset:52224
	v_add_co_u32_e32 v34, vcc, s1, v38
	s_mov_b32 s1, 0xc000
	s_nop 0
	v_addc_co_u32_e32 v35, vcc, 0, v39, vcc
	ds_write_b128 v142, v[104:107] offset:56576
	v_add_co_u32_e32 v34, vcc, s1, v38
	s_mov_b32 s1, 0xe000
	s_nop 0
	v_addc_co_u32_e32 v35, vcc, 0, v39, vcc
	ds_write_b128 v142, v[108:111] offset:60928
	v_add_co_u32_e32 v34, vcc, s1, v38
	v_readlane_b32 s1, v254, 62
	s_nop 0
	v_addc_co_u32_e32 v35, vcc, 0, v39, vcc
	ds_write_b128 v142, v[112:115] offset:65280
	v_mov_b32_e32 v34, v0
	s_nop 0
	v_and_b32_e32 v36, 0x7f, v34
	v_or_b32_e32 v36, s10, v36
	v_ashrrev_i32_e32 v37, 31, v36
	v_ashrrev_i32_e32 v38, 3, v34
	v_and_b32_e32 v38, -16, v38
	v_lshlrev_b64 v[36:37], 7, v[36:37]
	v_ashrrev_i32_e32 v39, 31, v38
	v_lshl_add_u64 v[36:37], s[30:31], 0, v[36:37]
	v_lshl_add_u64 v[36:37], v[38:39], 2, v[36:37]
	v_lshl_add_u64 v[36:37], v[36:37], 0, s[88:89]
	v_add_u32_e32 v36, s1, v38
	v_or_b32_e32 v36, s14, v36
	v_ashrrev_i32_e32 v37, 31, v36
	v_lshl_add_u64 v[36:37], v[36:37], 2, s[60:61]
	v_and_b32_e32 v35, 63, v34
	v_mul_f32_e32 v37, 0x3fb8aa3b, v50
	v_fma_f32 v38, v50, s96, -v37
	v_rndne_f32_e32 v40, v37
	v_fmac_f32_e32 v38, 0x32a5705f, v50
	v_sub_f32_e32 v37, v37, v40
	v_add_f32_e32 v37, v37, v38
	v_exp_f32_e32 v37, v37
	v_cvt_i32_f32_e32 v38, v40
	v_cmp_ngt_f32_e32 vcc, s97, v50
	v_and_b32_e32 v40, 64, v198
	v_ldexp_f32 v37, v37, v38
	v_mov_b32_e32 v38, 0x11400
	v_lshl_add_u32 v38, v34, 2, v38
	v_cndmask_b32_e32 v37, 0, v37, vcc
	v_cmp_nlt_f32_e32 vcc, s26, v50
	ds_write_b32 v38, v51
	v_add_u32_e32 v38, -1, v198
	v_cndmask_b32_e32 v37, v208, v37, vcc
	v_cmp_lt_i32_e32 vcc, v38, v40
	v_mul_f32_e64 v36, v51, -v37
	s_nop 0
	v_cndmask_b32_e32 v38, v38, v198, vcc
	v_lshlrev_b32_e32 v38, 2, v38
	ds_bpermute_b32 v38, v38, v36
	v_cmp_eq_u32_e32 vcc, 0, v35
	s_waitcnt lgkmcnt(0)
	v_fma_f32 v37, v51, -v37, v38
	v_add_u32_e32 v38, -2, v198
	v_cndmask_b32_e32 v37, v37, v36, vcc
	v_cmp_lt_i32_e32 vcc, v38, v40
	s_nop 1
	v_cndmask_b32_e32 v38, v38, v198, vcc
	v_lshlrev_b32_e32 v38, 2, v38
	ds_bpermute_b32 v38, v38, v37
	v_cmp_gt_u32_e32 vcc, 2, v35
	s_waitcnt lgkmcnt(0)
	v_add_f32_e32 v38, v37, v38
	v_cndmask_b32_e32 v37, v38, v37, vcc
	v_add_u32_e32 v38, -4, v198
	v_cmp_lt_i32_e32 vcc, v38, v40
	s_nop 1
	v_cndmask_b32_e32 v38, v38, v198, vcc
	v_lshlrev_b32_e32 v38, 2, v38
	ds_bpermute_b32 v38, v38, v37
	v_cmp_gt_u32_e32 vcc, 4, v35
	s_waitcnt lgkmcnt(0)
	v_add_f32_e32 v38, v37, v38
	v_cndmask_b32_e32 v37, v38, v37, vcc
	v_add_u32_e32 v38, -8, v198
	v_cmp_lt_i32_e32 vcc, v38, v40
	s_nop 1
	v_cndmask_b32_e32 v38, v38, v198, vcc
	v_lshlrev_b32_e32 v38, 2, v38
	ds_bpermute_b32 v38, v38, v37
	v_cmp_gt_u32_e32 vcc, 8, v35
	s_waitcnt lgkmcnt(0)
	v_add_f32_e32 v38, v37, v38
	v_cndmask_b32_e32 v37, v38, v37, vcc
	v_add_u32_e32 v38, -16, v198
	v_cmp_lt_i32_e32 vcc, v38, v40
	s_nop 1
	v_cndmask_b32_e32 v38, v38, v198, vcc
	v_lshlrev_b32_e32 v38, 2, v38
	ds_bpermute_b32 v38, v38, v37
	v_cmp_gt_u32_e32 vcc, 16, v35
	s_waitcnt lgkmcnt(0)
	v_add_f32_e32 v38, v37, v38
	v_cndmask_b32_e32 v37, v38, v37, vcc
	v_subrev_u32_e32 v38, 32, v198
	v_cmp_lt_i32_e32 vcc, v38, v40
	s_nop 1
	v_cndmask_b32_e32 v38, v38, v198, vcc
	v_lshlrev_b32_e32 v38, 2, v38
	ds_bpermute_b32 v38, v38, v37
	v_cmp_eq_u32_e32 vcc, 63, v35
	s_waitcnt lgkmcnt(0)
	v_add_f32_e32 v39, v37, v38
	v_ashrrev_i32_e32 v38, 6, v34
	s_and_saveexec_b64 s[6:7], vcc
	v_mov_b32_e32 v40, 0x11000
	v_lshl_add_u32 v40, v38, 2, v40
	ds_write_b32 v40, v39
	s_or_b64 exec, exec, s[6:7]
	v_and_b32_e32 v40, 64, v34
	v_cmp_ne_u32_e32 vcc, 0, v40
	v_mov_b32_e32 v40, 0
	s_waitcnt lgkmcnt(0)
	s_barrier
	s_and_saveexec_b64 s[6:7], vcc
	v_mov_b32_e32 v40, 0x10ffc
	v_lshl_add_u32 v40, v38, 2, v40
	ds_read_b32 v40, v40
	s_or_b64 exec, exec, s[6:7]
	v_cmp_gt_u32_e32 vcc, 32, v35
	s_movk_i32 s1, 0x7f
	s_nop 0
	v_cndmask_b32_e32 v35, v39, v37, vcc
	s_waitcnt lgkmcnt(0)
	v_add_f32_e32 v35, v35, v40
	v_cmp_lt_u32_e32 vcc, s1, v34
	s_and_saveexec_b64 s[6:7], vcc
	s_cbranch_execz .LBB0_186
	v_and_b32_e32 v37, 0x3ffffffe, v38
	v_mov_b32_e32 v39, 0x11000
	v_lshl_or_b32 v38, v38, 2, 4
	v_lshl_add_u32 v37, v37, 2, v39
	v_add_u32_e32 v38, 0x11000, v38
	ds_read_b32 v37, v37
	ds_read_b32 v38, v38
	s_waitcnt lgkmcnt(0)
	v_add_f32_e32 v37, v37, v38
	v_sub_f32_e32 v35, v37, v35
	v_add_f32_e32 v35, v36, v35

.LBB0_577:
	v_or_b32_e32 v112, s0, v1
	v_ashrrev_i32_e32 v113, 31, v112
	v_lshlrev_b64 v[114:115], 11, v[112:113]
	v_lshl_add_u64 v[116:117], v[82:83], 0, v[114:115]
	s_movk_i32 s27, 0x4000
	v_readlane_b32 s28, v253, 55
	v_cmp_gt_i32_e32 vcc, s27, v112
	v_add_u32_e32 v114, 0xffffc000, v112
	v_mov_b32_e32 v115, s40
	v_mov_b32_e32 v118, s36
	v_mov_b32_e32 v119, s41
	v_mov_b32_e32 v120, s37
	v_mov_b32_e32 v121, s87
	v_mov_b32_e32 v122, s85
	v_mov_b32_e32 v123, s86
	v_mov_b32_e32 v124, s84
	global_load_dwordx2 v[126:127], v[116:117], off
	global_load_dwordx2 v[128:129], v[116:117], off offset:512
	global_load_dwordx2 v[138:139], v[116:117], off offset:1024
	global_load_dwordx2 v[140:141], v[116:117], off offset:1536
	v_readlane_b32 s32, v253, 56
	v_or_b32_e32 v116, 1, v112
	v_cndmask_b32_e32 v117, 0, v113, vcc
	v_cndmask_b32_e32 v125, v114, v112, vcc
	v_cndmask_b32_e32 v114, v115, v118, vcc
	v_cndmask_b32_e32 v134, v119, v120, vcc
	v_cndmask_b32_e32 v137, v121, v122, vcc
	v_cndmask_b32_e32 v142, v123, v124, vcc
	s_mov_b32 s62, s28
	s_mov_b32 s63, s32
	v_lshl_add_u64 v[144:145], v[112:113], 2, s[62:63]
	v_ashrrev_i32_e32 v113, 31, v116
	v_cmp_gt_i32_e32 vcc, s27, v116
	v_add_u32_e32 v143, 0xffffc001, v112
	v_mov_b32_e32 v146, v116
	v_mov_b32_e32 v147, v113
	v_lshlrev_b64 v[148:149], 11, v[146:147]
	v_cndmask_b32_e32 v112, 0, v113, vcc
	v_cndmask_b32_e32 v113, v143, v116, vcc
	v_cndmask_b32_e32 v116, v115, v118, vcc
	v_cndmask_b32_e32 v115, v119, v120, vcc
	v_cndmask_b32_e32 v118, v121, v122, vcc
	v_cndmask_b32_e32 v119, v123, v124, vcc
	v_cndmask_b32_e64 v120, v118, v115, s[2:3]
	v_cndmask_b32_e64 v115, v119, v116, s[2:3]
	v_mov_b32_e32 v118, v113
	v_mov_b32_e32 v119, v112
	v_lshlrev_b64 v[122:123], 12, v[118:119]
	v_cndmask_b32_e64 v112, v137, v134, s[2:3]
	v_cndmask_b32_e64 v113, v142, v114, s[2:3]
	v_mov_b32_e32 v118, v125
	v_mov_b32_e32 v119, v117
	v_lshlrev_b64 v[142:143], 12, v[118:119]
	v_mov_b32_e32 v116, v115
	v_mov_b32_e32 v117, v120
	v_lshl_add_u64 v[118:119], v[116:117], 0, v[122:123]
	s_mov_b32 s27, 0x11000
	v_mov_b32_e32 v114, v113
	v_mov_b32_e32 v115, v112
	v_lshl_add_u64 v[116:117], v[114:115], 0, v[142:143]
	v_lshl_add_u64 v[112:113], v[82:83], 0, v[148:149]
	v_lshl_add_u64 v[114:115], v[118:119], 0, v[130:131]
	v_add_co_u32_e32 v118, vcc, s27, v144
	v_lshl_add_u64 v[120:121], v[116:117], 0, v[130:131]
	global_load_dwordx2 v[116:117], v[112:113], off
	global_load_dwordx4 v[122:125], v[114:115], off
	global_load_dwordx2 v[142:143], v[112:113], off offset:512
	global_load_dwordx4 v[146:149], v[114:115], off offset:1024
	global_load_dwordx2 v[150:151], v[112:113], off offset:1024
	global_load_dwordx4 v[152:155], v[114:115], off offset:2048
	global_load_dwordx2 v[156:157], v[112:113], off offset:1536
	global_load_dwordx4 v[162:165], v[114:115], off offset:3072
	global_load_dwordx2 v[112:113], v[144:145], off
	v_addc_co_u32_e32 v114, vcc, 0, v145, vcc
	v_mov_b32_e32 v158, v118
	v_mov_b32_e32 v159, v114
	global_load_dwordx2 v[168:169], v[158:159], off
	s_mov_b32 s27, 0x22000
	global_load_dwordx4 v[174:177], v[120:121], off
	v_add_co_u32_e32 v114, vcc, s27, v144
	s_mov_b32 s27, 0x33000
	s_nop 0
	v_addc_co_u32_e32 v115, vcc, 0, v145, vcc
	global_load_dwordx2 v[118:119], v[114:115], off
	v_add_co_u32_e32 v114, vcc, s27, v144
	s_mov_b32 s27, 0x44000
	s_nop 0
	v_addc_co_u32_e32 v115, vcc, 0, v145, vcc
	global_load_dwordx2 v[158:159], v[114:115], off
	v_add_co_u32_e32 v114, vcc, s27, v144
	s_mov_b32 s27, 0x55000
	s_nop 0
	v_addc_co_u32_e32 v115, vcc, 0, v145, vcc
	global_load_dwordx2 v[170:171], v[114:115], off
	v_add_co_u32_e32 v114, vcc, s27, v144
	s_mov_b32 s27, 0x66000
	s_nop 0
	v_addc_co_u32_e32 v115, vcc, 0, v145, vcc
	global_load_dwordx2 v[180:181], v[114:115], off
	v_add_co_u32_e32 v114, vcc, s27, v144
	s_mov_b32 s27, 0x77000
	s_nop 0
	v_addc_co_u32_e32 v115, vcc, 0, v145, vcc
	global_load_dwordx2 v[182:183], v[114:115], off
	v_add_co_u32_e32 v114, vcc, s27, v144
	s_mov_b32 s27, 0x88000
	s_nop 0
	v_addc_co_u32_e32 v115, vcc, 0, v145, vcc
	global_load_dwordx2 v[184:185], v[114:115], off
	v_add_co_u32_e32 v114, vcc, s27, v144
	s_mov_b32 s27, 0x99000
	s_nop 0
	v_addc_co_u32_e32 v115, vcc, 0, v145, vcc
	global_load_dwordx2 v[186:187], v[114:115], off
	v_add_co_u32_e32 v114, vcc, s27, v144
	s_mov_b32 s27, 0xaa000
	s_nop 0
	v_addc_co_u32_e32 v115, vcc, 0, v145, vcc
	global_load_dwordx2 v[188:189], v[114:115], off
	v_add_co_u32_e32 v114, vcc, s27, v144
	s_mov_b32 s27, 0xbb000
	s_nop 0
	v_addc_co_u32_e32 v115, vcc, 0, v145, vcc
	global_load_dwordx2 v[190:191], v[114:115], off
	v_add_co_u32_e32 v114, vcc, s27, v144
	s_mov_b32 s27, 0xcc000
	s_nop 0
	v_addc_co_u32_e32 v115, vcc, 0, v145, vcc
	global_load_dwordx2 v[192:193], v[114:115], off
	v_add_co_u32_e32 v114, vcc, s27, v144
	s_mov_b32 s27, 0xdd000
	s_nop 0
	v_addc_co_u32_e32 v115, vcc, 0, v145, vcc
	global_load_dwordx2 v[194:195], v[114:115], off
	v_add_co_u32_e32 v114, vcc, s27, v144
	s_mov_b32 s27, 0xee000
	s_nop 0
	v_addc_co_u32_e32 v115, vcc, 0, v145, vcc
	global_load_dwordx2 v[212:213], v[114:115], off
	v_add_co_u32_e32 v114, vcc, s27, v144
	s_mov_b32 s27, 0xff000
	s_nop 0
	v_addc_co_u32_e32 v115, vcc, 0, v145, vcc
	v_add_co_u32_e32 v134, vcc, s27, v144
	global_load_dwordx2 v[214:215], v[114:115], off
	s_nop 0
	v_addc_co_u32_e32 v114, vcc, 0, v145, vcc
	v_mov_b32_e32 v144, v134
	v_mov_b32_e32 v145, v114
	global_load_dwordx2 v[218:219], v[144:145], off
	global_load_dwordx4 v[220:223], v[120:121], off offset:1024
	global_load_dwordx4 v[224:227], v[120:121], off offset:2048
	global_load_dwordx4 v[228:231], v[120:121], off offset:3072
	v_or_b32_e32 v34, s0, v1
	v_ashrrev_i32_e32 v35, 31, v34
	v_lshlrev_b64 v[88:89], 11, v[34:35]
	v_lshl_add_u64 v[36:37], v[82:83], 0, v[88:89]
	s_movk_i32 s6, 0x4000
	v_readlane_b32 s0, v253, 55
	v_cmp_gt_i32_e32 vcc, s6, v34
	v_add_u32_e32 v38, 0xffffc000, v34
	v_mov_b32_e32 v42, s40
	v_mov_b32_e32 v43, s36
	v_mov_b32_e32 v44, s41
	v_mov_b32_e32 v45, s37
	v_mov_b32_e32 v46, s87
	v_mov_b32_e32 v47, s85
	v_mov_b32_e32 v48, s86
	v_mov_b32_e32 v49, s84
	v_readlane_b32 s1, v253, 56
	v_or_b32_e32 v36, 1, v34
	v_cndmask_b32_e32 v39, 0, v35, vcc
	v_cndmask_b32_e32 v38, v38, v34, vcc
	v_cndmask_b32_e32 v40, v42, v43, vcc
	v_cndmask_b32_e32 v41, v44, v45, vcc
	v_cndmask_b32_e32 v51, v46, v47, vcc
	v_cndmask_b32_e32 v50, v48, v49, vcc
	v_lshl_add_u64 v[58:59], v[34:35], 2, s[0:1]
	v_ashrrev_i32_e32 v37, 31, v36
	v_cmp_gt_i32_e32 vcc, s6, v36
	v_add_u32_e32 v34, 0xffffc001, v34
	v_lshlrev_b64 v[86:87], 11, v[36:37]
	v_cndmask_b32_e32 v35, 0, v37, vcc
	v_cndmask_b32_e32 v34, v34, v36, vcc
	v_cndmask_b32_e32 v36, v42, v43, vcc
	v_cndmask_b32_e32 v37, v44, v45, vcc
	v_cndmask_b32_e32 v97, v46, v47, vcc
	v_cndmask_b32_e32 v96, v48, v49, vcc
	v_cndmask_b32_e64 v37, v97, v37, s[2:3]
	v_cndmask_b32_e64 v36, v96, v36, s[2:3]
	v_lshlrev_b64 v[98:99], 12, v[34:35]
	v_cndmask_b32_e64 v41, v51, v41, s[2:3]
	v_cndmask_b32_e64 v40, v50, v40, s[2:3]
	v_lshlrev_b64 v[54:55], 12, v[38:39]
	v_lshl_add_u64 v[34:35], v[36:37], 0, v[98:99]
	s_mov_b32 s0, 0x11000
	v_lshl_add_u64 v[38:39], v[40:41], 0, v[54:55]
	v_lshl_add_u64 v[64:65], v[82:83], 0, v[86:87]
	v_lshl_add_u64 v[34:35], v[34:35], 0, v[130:131]
	v_add_co_u32_e32 v104, vcc, s0, v58
	v_lshl_add_u64 v[62:63], v[38:39], 0, v[130:131]
	s_waitcnt vmcnt(0)
	v_mov_b32_e32 v92, v116
	v_mov_b32_e32 v93, v117
	v_mov_b32_e32 v38, v122
	v_mov_b32_e32 v39, v123
	v_mov_b32_e32 v40, v124
	v_mov_b32_e32 v41, v125
	v_mov_b32_e32 v100, v142
	v_mov_b32_e32 v101, v143
	v_mov_b32_e32 v46, v146
	v_mov_b32_e32 v47, v147
	v_mov_b32_e32 v48, v148
	v_mov_b32_e32 v49, v149
	v_mov_b32_e32 v94, v150
	v_mov_b32_e32 v95, v151
	v_mov_b32_e32 v42, v152
	v_mov_b32_e32 v43, v153
	v_mov_b32_e32 v44, v154
	v_mov_b32_e32 v45, v155
	v_mov_b32_e32 v90, v156
	v_mov_b32_e32 v91, v157
	s_nop 0
	v_mov_b32_e32 v34, v162
	v_mov_b32_e32 v35, v163
	v_mov_b32_e32 v36, v164
	v_mov_b32_e32 v37, v165
	s_nop 0
	v_addc_co_u32_e32 v105, vcc, 0, v59, vcc
	s_mov_b32 s0, 0x22000
	v_lshl_add_u64 v[50:51], v[50:51], 0, v[54:55]
	v_lshl_add_u64 v[106:107], v[50:51], 0, v[130:131]
	v_lshlrev_b32_e32 v50, 16, v126
	v_and_b32_e32 v51, 0xffff0000, v126
	v_lshlrev_b32_e32 v52, 16, v127
	v_and_b32_e32 v53, 0xffff0000, v127
	v_lshlrev_b32_e32 v54, 16, v128
	v_and_b32_e32 v55, 0xffff0000, v128
	v_lshlrev_b32_e32 v56, 16, v129
	v_and_b32_e32 v57, 0xffff0000, v129
	v_pk_add_f32 v[64:65], v[112:113], 0 op_sel_hi:[1,0]
	v_pk_add_f32 v[64:65], v[64:65], v[168:169]
	v_add_co_u32_e32 v104, vcc, s0, v58
	s_mov_b32 s0, 0x33000
	s_nop 0
	v_addc_co_u32_e32 v105, vcc, 0, v59, vcc
	v_pk_add_f32 v[64:65], v[64:65], v[118:119]
	v_add_co_u32_e32 v104, vcc, s0, v58
	s_mov_b32 s0, 0x44000
	s_nop 0
	v_addc_co_u32_e32 v105, vcc, 0, v59, vcc
	v_pk_add_f32 v[64:65], v[64:65], v[158:159]
	v_add_co_u32_e32 v104, vcc, s0, v58
	s_mov_b32 s0, 0x55000
	s_nop 0
	v_addc_co_u32_e32 v105, vcc, 0, v59, vcc
	v_pk_add_f32 v[64:65], v[64:65], v[170:171]
	v_add_co_u32_e32 v104, vcc, s0, v58
	s_mov_b32 s0, 0x66000
	s_nop 0
	v_addc_co_u32_e32 v105, vcc, 0, v59, vcc
	v_pk_add_f32 v[64:65], v[64:65], v[180:181]
	v_add_co_u32_e32 v104, vcc, s0, v58
	s_mov_b32 s0, 0x77000
	s_nop 0
	v_addc_co_u32_e32 v105, vcc, 0, v59, vcc
	v_pk_add_f32 v[64:65], v[64:65], v[182:183]
	v_add_co_u32_e32 v104, vcc, s0, v58
	s_mov_b32 s0, 0x88000
	s_nop 0
	v_addc_co_u32_e32 v105, vcc, 0, v59, vcc
	v_pk_add_f32 v[64:65], v[64:65], v[184:185]
	v_add_co_u32_e32 v104, vcc, s0, v58
	s_mov_b32 s0, 0x99000
	s_nop 0
	v_addc_co_u32_e32 v105, vcc, 0, v59, vcc
	v_pk_add_f32 v[64:65], v[64:65], v[186:187]
	v_add_co_u32_e32 v104, vcc, s0, v58
	s_mov_b32 s0, 0xaa000
	s_nop 0
	v_addc_co_u32_e32 v105, vcc, 0, v59, vcc
	v_pk_add_f32 v[64:65], v[64:65], v[188:189]
	v_add_co_u32_e32 v104, vcc, s0, v58
	s_mov_b32 s0, 0xbb000
	s_nop 0
	v_addc_co_u32_e32 v105, vcc, 0, v59, vcc
	v_pk_add_f32 v[64:65], v[64:65], v[190:191]
	v_add_co_u32_e32 v104, vcc, s0, v58
	s_mov_b32 s0, 0xcc000
	s_nop 0
	v_addc_co_u32_e32 v105, vcc, 0, v59, vcc
	v_pk_add_f32 v[64:65], v[64:65], v[192:193]
	v_add_co_u32_e32 v104, vcc, s0, v58
	s_mov_b32 s0, 0xdd000
	s_nop 0
	v_addc_co_u32_e32 v105, vcc, 0, v59, vcc
	v_pk_add_f32 v[64:65], v[64:65], v[194:195]
	v_add_co_u32_e32 v104, vcc, s0, v58
	s_mov_b32 s0, 0xee000
	s_nop 0
	v_addc_co_u32_e32 v105, vcc, 0, v59, vcc
	v_pk_add_f32 v[64:65], v[64:65], v[212:213]
	v_add_co_u32_e32 v104, vcc, s0, v58
	s_mov_b32 s0, 0xff000
	s_nop 0
	v_addc_co_u32_e32 v105, vcc, 0, v59, vcc
	v_add_co_u32_e32 v58, vcc, s0, v58
	s_nop 0
	v_addc_co_u32_e32 v59, vcc, 0, v59, vcc
	s_mov_b32 s0, 0x3a800000
	v_pk_add_f32 v[64:65], v[64:65], v[214:215]
	v_pk_add_f32 v[58:59], v[64:65], v[218:219]
	s_nop 0
	v_pk_fma_f32 v[104:105], v[58:59], s[0:1], v[132:133] op_sel_hi:[1,0,0]
	s_mov_b32 s0, 0x800000
	v_mul_f32_e32 v58, 0x4b800000, v104
	v_cmp_gt_f32_e32 vcc, s0, v104
	v_cmp_gt_f32_e64 s[6:7], s0, v105
	s_nop 0
	v_cndmask_b32_e32 v58, v104, v58, vcc
	v_rsq_f32_e32 v58, v58
	s_nop 0
	v_mul_f32_e32 v59, 0x45800000, v58
	v_cndmask_b32_e32 v104, v58, v59, vcc
	v_pk_mul_f32 v[50:51], v[104:105], v[50:51] op_sel_hi:[0,1]
	v_pk_mul_f32 v[52:53], v[104:105], v[52:53] op_sel_hi:[0,1]
	v_pk_fma_f32 v[50:51], v[66:67], v[50:51], v[174:175]
	v_pk_fma_f32 v[52:53], v[68:69], v[52:53], v[176:177]
	v_pk_mul_f32 v[54:55], v[104:105], v[54:55] op_sel_hi:[0,1]
	v_pk_mul_f32 v[56:57], v[104:105], v[56:57] op_sel_hi:[0,1]
	v_lshlrev_b32_e32 v58, 16, v138
	v_and_b32_e32 v59, 0xffff0000, v138
	v_pk_mul_f32 v[58:59], v[104:105], v[58:59] op_sel_hi:[0,1]
	v_lshlrev_b32_e32 v60, 16, v139
	v_and_b32_e32 v61, 0xffff0000, v139
	v_pk_mul_f32 v[60:61], v[104:105], v[60:61] op_sel_hi:[0,1]
	s_and_b64 vcc, exec, s[4:5]
	v_pk_fma_f32 v[54:55], v[70:71], v[54:55], v[220:221]
	v_pk_fma_f32 v[56:57], v[72:73], v[56:57], v[222:223]
	v_mov_b32_e32 v108, v224
	v_mov_b32_e32 v109, v225
	v_mov_b32_e32 v110, v226
	v_mov_b32_e32 v111, v227
	v_pk_fma_f32 v[58:59], v[74:75], v[58:59], v[108:109]
	v_lshlrev_b32_e32 v108, 16, v140
	v_and_b32_e32 v109, 0xffff0000, v140
	v_lshlrev_b32_e32 v102, 16, v141
	v_and_b32_e32 v103, 0xffff0000, v141
	v_pk_mul_f32 v[108:109], v[104:105], v[108:109] op_sel_hi:[0,1]
	v_pk_mul_f32 v[102:103], v[104:105], v[102:103] op_sel_hi:[0,1]
	v_pk_fma_f32 v[60:61], v[76:77], v[60:61], v[110:111]
	global_store_dwordx4 v[106:107], v[50:53], off
	global_store_dwordx4 v[106:107], v[54:57], off offset:1024
	global_store_dwordx4 v[106:107], v[58:61], off offset:2048
	v_pk_fma_f32 v[62:63], v[78:79], v[108:109], v[228:229]
	v_pk_fma_f32 v[64:65], v[80:81], v[102:103], v[230:231]
	global_store_dwordx4 v[106:107], v[62:65], off offset:3072
	s_cbranch_vccnz .LBB0_579
	v_mov_b32_e32 v108, v51
	v_mov_b32_e32 v109, v55
	v_mov_b32_e32 v106, v50
	v_mov_b32_e32 v107, v54
	v_pk_mul_f32 v[108:109], v[108:109], v[108:109]
	v_mov_b32_e32 v110, v63
	v_pk_fma_f32 v[106:107], v[106:107], v[106:107], v[108:109]
	v_mov_b32_e32 v108, v52
	v_mov_b32_e32 v109, v56
	v_mov_b32_e32 v111, v59
	v_pk_fma_f32 v[106:107], v[108:109], v[108:109], v[106:107]
	v_mov_b32_e32 v108, v62
	v_mov_b32_e32 v109, v58
	v_pk_mul_f32 v[110:111], v[110:111], v[110:111]
	v_mov_b32_e32 v102, v53
	v_mov_b32_e32 v103, v57
	v_pk_fma_f32 v[108:109], v[108:109], v[108:109], v[110:111]
	v_mov_b32_e32 v110, v64
	v_mov_b32_e32 v111, v60
	v_pk_fma_f32 v[102:103], v[102:103], v[102:103], v[106:107]
	v_mov_b32_e32 v106, v65
	v_mov_b32_e32 v107, v61
	v_pk_fma_f32 v[108:109], v[110:111], v[110:111], v[108:109]
	v_add_f32_e32 v102, v102, v103
	v_pk_fma_f32 v[106:107], v[106:107], v[106:107], v[108:109]
	v_cmp_lt_i32_e32 vcc, v201, v200
	v_add_f32_e32 v102, v107, v102
	v_add_f32_e32 v102, v106, v102
	v_cndmask_b32_e32 v103, v198, v201, vcc
	v_lshlrev_b32_e32 v103, 2, v103
	ds_bpermute_b32 v103, v103, v102
	v_cmp_lt_i32_e32 vcc, v202, v200
	v_lshl_add_u64 v[88:89], v[84:85], 0, v[88:89]
	s_waitcnt lgkmcnt(0)
	v_add_f32_e32 v102, v102, v103
	v_cndmask_b32_e32 v103, v198, v202, vcc
	v_lshlrev_b32_e32 v103, 2, v103
	ds_bpermute_b32 v103, v103, v102
	v_cmp_lt_i32_e32 vcc, v203, v200
	s_waitcnt lgkmcnt(0)
	v_add_f32_e32 v102, v102, v103
	v_cndmask_b32_e32 v103, v198, v203, vcc
	v_lshlrev_b32_e32 v103, 2, v103
	ds_bpermute_b32 v103, v103, v102
	v_cmp_lt_i32_e32 vcc, v204, v200
	s_waitcnt lgkmcnt(0)
	v_add_f32_e32 v102, v102, v103
	v_cndmask_b32_e32 v103, v198, v204, vcc
	v_lshlrev_b32_e32 v103, 2, v103
	ds_bpermute_b32 v103, v103, v102
	v_cmp_lt_i32_e32 vcc, v205, v200
	s_waitcnt lgkmcnt(0)
	v_add_f32_e32 v102, v102, v103
	v_cndmask_b32_e32 v103, v198, v205, vcc
	v_lshlrev_b32_e32 v103, 2, v103
	ds_bpermute_b32 v103, v103, v102
	v_cmp_lt_i32_e32 vcc, v206, v200
	s_waitcnt lgkmcnt(0)
	v_add_f32_e32 v102, v102, v103
	v_cndmask_b32_e32 v103, v198, v206, vcc
	v_lshlrev_b32_e32 v103, 2, v103
	ds_bpermute_b32 v103, v103, v102
	s_waitcnt lgkmcnt(0)
	v_add_f32_e32 v102, v102, v103
	v_fmamk_f32 v102, v102, 0x3a800000, v132
	v_mul_f32_e32 v103, 0x4b800000, v102
	v_cmp_gt_f32_e32 vcc, s0, v102
	s_nop 1
	v_cndmask_b32_e32 v102, v102, v103, vcc
	v_rsq_f32_e32 v102, v102
	s_nop 0
	v_mul_f32_e32 v103, 0x45800000, v102
	v_cndmask_b32_e32 v102, v102, v103, vcc
	v_pk_mul_f32 v[50:51], v[50:51], v[102:103] op_sel_hi:[1,0]
	v_pk_mul_f32 v[52:53], v[52:53], v[102:103] op_sel_hi:[1,0]
	v_pk_fma_f32 v[50:51], v[6:7], v[50:51], v[2:3]
	v_pk_fma_f32 v[52:53], v[8:9], v[52:53], v[4:5]
	v_cvt_pk_bf16_f32 v50, v50, v51
	v_cvt_pk_bf16_f32 v51, v52, v53
	global_store_dwordx2 v[88:89], v[50:51], off
	v_pk_mul_f32 v[50:51], v[54:55], v[102:103] op_sel_hi:[1,0]
	v_pk_mul_f32 v[52:53], v[56:57], v[102:103] op_sel_hi:[1,0]
	v_pk_fma_f32 v[50:51], v[14:15], v[50:51], v[10:11]
	v_pk_fma_f32 v[52:53], v[16:17], v[52:53], v[12:13]
	v_cvt_pk_bf16_f32 v50, v50, v51
	v_cvt_pk_bf16_f32 v51, v52, v53
	global_store_dwordx2 v[88:89], v[50:51], off offset:512
	v_pk_mul_f32 v[50:51], v[58:59], v[102:103] op_sel_hi:[1,0]
	v_pk_mul_f32 v[52:53], v[60:61], v[102:103] op_sel_hi:[1,0]
	v_pk_fma_f32 v[50:51], v[22:23], v[50:51], v[18:19]
	v_pk_fma_f32 v[52:53], v[24:25], v[52:53], v[20:21]
	v_cvt_pk_bf16_f32 v50, v50, v51
	v_cvt_pk_bf16_f32 v51, v52, v53
	global_store_dwordx2 v[88:89], v[50:51], off offset:1024
	v_pk_mul_f32 v[50:51], v[62:63], v[102:103] op_sel_hi:[1,0]
	v_pk_mul_f32 v[52:53], v[64:65], v[102:103] op_sel_hi:[1,0]
	v_pk_fma_f32 v[50:51], v[30:31], v[50:51], v[26:27]
	v_pk_fma_f32 v[52:53], v[32:33], v[52:53], v[28:29]
	v_cvt_pk_bf16_f32 v50, v50, v51
	v_cvt_pk_bf16_f32 v51, v52, v53
	global_store_dwordx2 v[88:89], v[50:51], off offset:1536

.LBB0_859:
	v_readlane_b32 s2, v254, 19
	s_add_i32 s2, s2, 1
	s_nop 0
	v_writelane_b32 v254, s2, 19
	s_waitcnt vmcnt(0)
	s_barrier
	s_and_saveexec_b64 s[2:3], s[12:13]
	s_cbranch_execnz .LBB0_860
	s_getpc_b64 s[98:99]

.LBB0_1063:
	v_lshl_add_u64 v[64:65], v[18:19], 0, s[0:1]
	global_load_dword v72, v[64:65], off
	s_movk_i32 s10, 0x6000
	v_add_co_u32_e32 v73, vcc, s7, v64
	s_nop 1
	v_addc_co_u32_e32 v74, vcc, 0, v65, vcc
	v_mov_b32_e32 v82, v73
	v_mov_b32_e32 v83, v74
	global_load_dword v75, v[82:83], off
	v_add_co_u32_e32 v73, vcc, s10, v64
	s_nop 1
	v_addc_co_u32_e32 v74, vcc, 0, v65, vcc
	v_mov_b32_e32 v82, v73
	v_mov_b32_e32 v83, v74
	global_load_dword v76, v[82:83], off
	s_mov_b32 s10, 0x9000
	v_add_co_u32_e32 v73, vcc, s10, v64
	s_nop 1
	v_addc_co_u32_e32 v74, vcc, 0, v65, vcc
	v_mov_b32_e32 v82, v73
	v_mov_b32_e32 v83, v74
	global_load_dword v78, v[82:83], off
	s_mov_b32 s10, 0xf000
	v_add_co_u32_e32 v73, vcc, s6, v64
	s_nop 1
	v_addc_co_u32_e32 v74, vcc, 0, v65, vcc
	v_mov_b32_e32 v82, v73
	v_mov_b32_e32 v83, v74
	global_load_dword v84, v[82:83], off
	v_add_co_u32_e32 v73, vcc, s10, v64
	s_mov_b32 s10, 0x12000
	s_nop 0
	v_addc_co_u32_e32 v74, vcc, 0, v65, vcc
	v_add_co_u32_e32 v82, vcc, s10, v64
	v_mov_b32_e32 v86, v73
	v_mov_b32_e32 v87, v74
	global_load_dword v83, v[86:87], off
	v_addc_co_u32_e32 v73, vcc, 0, v65, vcc
	v_mov_b32_e32 v86, v82
	v_mov_b32_e32 v87, v73
	global_load_dword v74, v[86:87], off
	s_mov_b32 s10, 0x15000
	v_add_co_u32_e32 v73, vcc, s10, v64
	s_nop 1
	v_addc_co_u32_e32 v82, vcc, 0, v65, vcc
	v_mov_b32_e32 v86, v73
	v_mov_b32_e32 v87, v82
	global_load_dword v85, v[86:87], off
	s_mov_b32 s10, 0x1b000
	v_add_co_u32_e32 v73, vcc, s5, v64
	s_nop 1
	v_addc_co_u32_e32 v82, vcc, 0, v65, vcc
	v_mov_b32_e32 v86, v73
	v_mov_b32_e32 v87, v82
	global_load_dword v88, v[86:87], off
	v_add_co_u32_e32 v73, vcc, s10, v64
	s_mov_b32 s10, 0x1e000
	s_nop 0
	v_addc_co_u32_e32 v82, vcc, 0, v65, vcc
	v_add_co_u32_e32 v86, vcc, s10, v64
	v_mov_b32_e32 v90, v73
	v_mov_b32_e32 v91, v82
	global_load_dword v87, v[90:91], off
	v_addc_co_u32_e32 v73, vcc, 0, v65, vcc
	v_mov_b32_e32 v90, v86
	v_mov_b32_e32 v91, v73
	global_load_dword v82, v[90:91], off
	s_mov_b32 s10, 0x21000
	v_add_co_u32_e32 v73, vcc, s10, v64
	s_nop 1
	v_addc_co_u32_e32 v86, vcc, 0, v65, vcc
	v_mov_b32_e32 v90, v73
	v_mov_b32_e32 v91, v86
	global_load_dword v89, v[90:91], off
	s_mov_b32 s10, 0x24000
	v_add_co_u32_e32 v73, vcc, s10, v64
	s_nop 1
	v_addc_co_u32_e32 v86, vcc, 0, v65, vcc
	v_mov_b32_e32 v90, v73
	v_mov_b32_e32 v91, v86
	global_load_dword v92, v[90:91], off
	s_mov_b32 s10, 0x27000
	v_add_co_u32_e32 v73, vcc, s10, v64
	s_mov_b32 s10, 0x2a000
	s_nop 0
	v_addc_co_u32_e32 v86, vcc, 0, v65, vcc
	v_add_co_u32_e32 v90, vcc, s10, v64
	v_mov_b32_e32 v94, v73
	v_mov_b32_e32 v95, v86
	global_load_dword v91, v[94:95], off
	v_addc_co_u32_e32 v73, vcc, 0, v65, vcc
	v_mov_b32_e32 v94, v90
	v_mov_b32_e32 v95, v73
	global_load_dword v86, v[94:95], off
	s_mov_b32 s10, 0x2d000
	v_add_co_u32_e32 v73, vcc, s10, v64
	s_nop 1
	v_addc_co_u32_e32 v90, vcc, 0, v65, vcc
	v_mov_b32_e32 v64, v73
	v_mov_b32_e32 v65, v90
	global_load_dword v93, v[64:65], off
	v_lshl_add_u64 v[20:21], v[18:19], 0, s[0:1]
	s_waitcnt vmcnt(0)
	v_mov_b32_e32 v48, v72
	ds_read_b128 v[28:31], v26
	ds_read_b128 v[10:13], v26 offset:16
	ds_read_b128 v[6:9], v26 offset:32
	ds_read_b128 v[2:5], v26 offset:48
	ds_read_b128 v[32:35], v26 offset:4096
	s_waitcnt lgkmcnt(4)
	v_mov_b32_e32 v36, v28
	s_movk_i32 s3, 0x6000
	s_add_u32 s0, s0, 0x30000
	s_addc_u32 s1, s1, 0
	s_waitcnt lgkmcnt(0)
	v_mov_b32_e32 v37, v32
	v_mov_b32_e32 v32, v29
	s_cmp_eq_u32 s0, 0x300000
	v_pk_fma_f32 v[24:25], v[48:49], v[36:37], v[24:25] op_sel_hi:[0,1,1]
	ds_read_b128 v[36:39], v26 offset:8192
	ds_read_b128 v[40:43], v26 offset:12288
	ds_read_b128 v[44:47], v26 offset:16384
	s_waitcnt lgkmcnt(2)
	v_mov_b32_e32 v50, v36
	s_waitcnt lgkmcnt(1)
	v_fmac_f32_e32 v17, v48, v40
	s_waitcnt lgkmcnt(0)
	v_mov_b32_e32 v51, v44
	v_pk_fma_f32 v[22:23], v[48:49], v[50:51], v[22:23] op_sel_hi:[0,1,1]
	v_add_co_u32_e32 v48, vcc, s7, v20
	v_mov_b32_e32 v44, v37
	s_nop 0
	v_addc_co_u32_e32 v49, vcc, 0, v21, vcc
	v_mov_b32_e32 v28, v75
	v_pk_fma_f32 v[24:25], v[28:29], v[32:33], v[24:25] op_sel_hi:[0,1,1]
	v_fmac_f32_e32 v17, v28, v41
	v_pk_fma_f32 v[22:23], v[28:29], v[44:45], v[22:23] op_sel_hi:[0,1,1]
	v_add_co_u32_e32 v28, vcc, s3, v20
	v_mov_b32_e32 v32, v30
	s_nop 0
	v_addc_co_u32_e32 v29, vcc, 0, v21, vcc
	v_mov_b32_e32 v28, v76
	v_mov_b32_e32 v33, v34
	s_mov_b32 s3, 0x9000
	v_mov_b32_e32 v34, v31
	v_pk_fma_f32 v[24:25], v[28:29], v[32:33], v[24:25] op_sel_hi:[0,1,1]
	v_mov_b32_e32 v32, v38
	v_mov_b32_e32 v33, v46
	v_fmac_f32_e32 v17, v28, v42
	v_pk_fma_f32 v[22:23], v[28:29], v[32:33], v[22:23] op_sel_hi:[0,1,1]
	v_add_co_u32_e32 v28, vcc, s3, v20
	v_mov_b32_e32 v46, v39
	s_nop 0
	v_addc_co_u32_e32 v29, vcc, 0, v21, vcc
	v_mov_b32_e32 v28, v78
	s_mov_b32 s3, 0xf000
	v_pk_fma_f32 v[40:41], v[28:29], v[46:47], v[22:23] op_sel_hi:[0,1,1]
	v_add_co_u32_e32 v22, vcc, s6, v20
	v_pk_fma_f32 v[30:31], v[28:29], v[34:35], v[24:25] op_sel_hi:[0,1,1]
	s_nop 0
	v_addc_co_u32_e32 v23, vcc, 0, v21, vcc
	v_mov_b32_e32 v42, v84
	ds_read_b128 v[22:25], v26 offset:4112
	v_fmac_f32_e32 v17, v28, v43
	v_mov_b32_e32 v28, v10
	s_waitcnt lgkmcnt(0)
	v_mov_b32_e32 v29, v22
	v_mov_b32_e32 v22, v11
	v_pk_fma_f32 v[44:45], v[42:43], v[28:29], v[30:31] op_sel_hi:[0,1,1]
	ds_read_b128 v[28:31], v26 offset:8208
	ds_read_b128 v[32:35], v26 offset:12304
	ds_read_b128 v[36:39], v26 offset:16400
	s_waitcnt lgkmcnt(2)
	v_mov_b32_e32 v46, v28
	s_waitcnt lgkmcnt(1)
	v_fmac_f32_e32 v17, v42, v32
	s_waitcnt lgkmcnt(0)
	v_mov_b32_e32 v47, v36
	v_pk_fma_f32 v[40:41], v[42:43], v[46:47], v[40:41] op_sel_hi:[0,1,1]
	v_add_co_u32_e32 v42, vcc, s3, v20
	s_mov_b32 s3, 0x12000
	s_nop 0
	v_addc_co_u32_e32 v43, vcc, 0, v21, vcc
	v_add_co_u32_e32 v28, vcc, s3, v20
	v_mov_b32_e32 v10, v83
	v_mov_b32_e32 v36, v29
	v_addc_co_u32_e32 v29, vcc, 0, v21, vcc
	v_mov_b32_e32 v28, v74
	v_mov_b32_e32 v32, v12
	s_mov_b32 s3, 0x15000
	v_pk_fma_f32 v[22:23], v[10:11], v[22:23], v[44:45] op_sel_hi:[0,1,1]
	v_fmac_f32_e32 v17, v10, v33
	v_mov_b32_e32 v33, v24
	v_pk_fma_f32 v[10:11], v[10:11], v[36:37], v[40:41] op_sel_hi:[0,1,1]
	v_pk_fma_f32 v[22:23], v[28:29], v[32:33], v[22:23] op_sel_hi:[0,1,1]
	v_mov_b32_e32 v32, v30
	v_mov_b32_e32 v33, v38
	v_fmac_f32_e32 v17, v28, v34
	v_pk_fma_f32 v[10:11], v[28:29], v[32:33], v[10:11] op_sel_hi:[0,1,1]
	v_add_co_u32_e32 v28, vcc, s3, v20
	v_mov_b32_e32 v38, v31
	s_nop 0
	v_addc_co_u32_e32 v29, vcc, 0, v21, vcc
	v_mov_b32_e32 v12, v85
	v_mov_b32_e32 v24, v13
	s_mov_b32 s3, 0x1b000
	v_pk_fma_f32 v[36:37], v[12:13], v[38:39], v[10:11] op_sel_hi:[0,1,1]
	v_add_co_u32_e32 v10, vcc, s5, v20
	v_pk_fma_f32 v[22:23], v[12:13], v[24:25], v[22:23] op_sel_hi:[0,1,1]
	s_nop 0
	v_addc_co_u32_e32 v11, vcc, 0, v21, vcc
	v_mov_b32_e32 v38, v88
	v_fmac_f32_e32 v17, v12, v35
	ds_read_b128 v[10:13], v26 offset:4128
	v_mov_b32_e32 v24, v6
	s_waitcnt lgkmcnt(0)
	v_mov_b32_e32 v25, v10
	v_mov_b32_e32 v10, v7
	v_pk_fma_f32 v[40:41], v[38:39], v[24:25], v[22:23] op_sel_hi:[0,1,1]
	ds_read_b128 v[22:25], v26 offset:8224
	ds_read_b128 v[28:31], v26 offset:12320
	ds_read_b128 v[32:35], v26 offset:16416
	s_waitcnt lgkmcnt(2)
	v_mov_b32_e32 v42, v22
	s_waitcnt lgkmcnt(1)
	v_fmac_f32_e32 v17, v38, v28
	s_waitcnt lgkmcnt(0)
	v_mov_b32_e32 v43, v32
	v_pk_fma_f32 v[36:37], v[38:39], v[42:43], v[36:37] op_sel_hi:[0,1,1]
	v_add_co_u32_e32 v38, vcc, s3, v20
	s_mov_b32 s3, 0x1e000
	s_nop 0
	v_addc_co_u32_e32 v39, vcc, 0, v21, vcc
	v_add_co_u32_e32 v22, vcc, s3, v20
	v_mov_b32_e32 v6, v87
	v_mov_b32_e32 v32, v23
	v_addc_co_u32_e32 v23, vcc, 0, v21, vcc
	v_mov_b32_e32 v22, v82
	v_mov_b32_e32 v28, v8
	s_mov_b32 s3, 0x21000
	v_pk_fma_f32 v[10:11], v[6:7], v[10:11], v[40:41] op_sel_hi:[0,1,1]
	v_fmac_f32_e32 v17, v6, v29
	v_mov_b32_e32 v29, v12
	v_pk_fma_f32 v[6:7], v[6:7], v[32:33], v[36:37] op_sel_hi:[0,1,1]
	v_pk_fma_f32 v[10:11], v[22:23], v[28:29], v[10:11] op_sel_hi:[0,1,1]
	v_mov_b32_e32 v28, v24
	v_mov_b32_e32 v29, v34
	v_fmac_f32_e32 v17, v22, v30
	v_pk_fma_f32 v[6:7], v[22:23], v[28:29], v[6:7] op_sel_hi:[0,1,1]
	v_add_co_u32_e32 v22, vcc, s3, v20
	v_mov_b32_e32 v34, v25
	s_nop 0
	v_addc_co_u32_e32 v23, vcc, 0, v21, vcc
	v_mov_b32_e32 v8, v89
	s_mov_b32 s3, 0x24000
	v_mov_b32_e32 v12, v9
	v_pk_fma_f32 v[22:23], v[8:9], v[34:35], v[6:7] op_sel_hi:[0,1,1]
	v_add_co_u32_e32 v6, vcc, s3, v20
	v_pk_fma_f32 v[10:11], v[8:9], v[12:13], v[10:11] op_sel_hi:[0,1,1]
	s_nop 0
	v_addc_co_u32_e32 v7, vcc, 0, v21, vcc
	v_mov_b32_e32 v24, v92
	v_fmac_f32_e32 v17, v8, v31
	ds_read_b128 v[6:9], v26 offset:4144
	v_mov_b32_e32 v12, v2
	s_mov_b32 s3, 0x27000
	s_waitcnt lgkmcnt(0)
	v_mov_b32_e32 v13, v6
	v_mov_b32_e32 v6, v3
	v_pk_fma_f32 v[36:37], v[24:25], v[12:13], v[10:11] op_sel_hi:[0,1,1]
	ds_read_b128 v[10:13], v26 offset:8240
	ds_read_b128 v[28:31], v26 offset:12336
	ds_read_b128 v[32:35], v26 offset:16432
	v_add_u32_e32 v26, 64, v26
	s_waitcnt lgkmcnt(2)
	v_mov_b32_e32 v38, v10
	s_waitcnt lgkmcnt(1)
	v_fmac_f32_e32 v17, v24, v28
	s_waitcnt lgkmcnt(0)
	v_mov_b32_e32 v39, v32
	v_pk_fma_f32 v[22:23], v[24:25], v[38:39], v[22:23] op_sel_hi:[0,1,1]
	v_add_co_u32_e32 v24, vcc, s3, v20
	s_mov_b32 s3, 0x2a000
	s_nop 0
	v_addc_co_u32_e32 v25, vcc, 0, v21, vcc
	v_add_co_u32_e32 v10, vcc, s3, v20
	v_mov_b32_e32 v2, v91
	v_mov_b32_e32 v32, v11
	v_addc_co_u32_e32 v11, vcc, 0, v21, vcc
	v_mov_b32_e32 v10, v86
	s_mov_b32 s3, 0x2d000
	v_pk_fma_f32 v[6:7], v[2:3], v[6:7], v[36:37] op_sel_hi:[0,1,1]
	v_fmac_f32_e32 v17, v2, v29
	v_pk_fma_f32 v[2:3], v[2:3], v[32:33], v[22:23] op_sel_hi:[0,1,1]
	v_mov_b32_e32 v22, v4
	v_mov_b32_e32 v23, v8
	v_pk_fma_f32 v[6:7], v[10:11], v[22:23], v[6:7] op_sel_hi:[0,1,1]
	v_mov_b32_e32 v22, v12
	v_mov_b32_e32 v23, v34
	v_fmac_f32_e32 v17, v10, v30
	v_pk_fma_f32 v[2:3], v[10:11], v[22:23], v[2:3] op_sel_hi:[0,1,1]
	v_add_co_u32_e32 v10, vcc, s3, v20
	v_mov_b32_e32 v8, v5
	s_nop 0
	v_addc_co_u32_e32 v11, vcc, 0, v21, vcc
	v_mov_b32_e32 v4, v93
	v_mov_b32_e32 v34, v13
	v_pk_fma_f32 v[24:25], v[4:5], v[8:9], v[6:7] op_sel_hi:[0,1,1]
	v_fmac_f32_e32 v17, v4, v31
	v_pk_fma_f32 v[22:23], v[4:5], v[34:35], v[2:3] op_sel_hi:[0,1,1]
	s_cbranch_scc0 .LBB0_1063
	s_movk_i32 s0, 0x500
	v_mul_lo_u32 v2, v15, s0
	s_movk_i32 s0, 0x140
	v_lshl_or_b32 v2, v1, 2, v2
	v_cmp_gt_i32_e32 vcc, s0, v14
	ds_write2st64_b32 v2, v24, v25 offset0:80 offset1:81
	ds_write2st64_b32 v2, v22, v17 offset0:82 offset1:83
	ds_write_b32 v2, v23 offset:21504
	s_waitcnt lgkmcnt(0)
	s_barrier
	s_and_saveexec_b64 s[0:1], vcc
	s_cbranch_execz .LBB0_1069
	s_mul_i32 s5, s4, 0xc00
	s_and_b32 s2, s2, 48
	s_cmp_eq_u32 s2, 16
	v_add_u32_e32 v4, s5, v16
	s_cselect_b64 s[2:3], -1, 0
	s_mul_i32 s6, s4, 5
	v_lshlrev_b32_e32 v130, 2, v4
	s_lshl_b32 s4, s4, 11
	v_lshl_add_u64 v[2:3], s[46:47], 0, v[130:131]
	v_subrev_u32_e32 v130, s4, v4
	v_readlane_b32 s4, v253, 25
	v_lshl_add_u64 v[4:5], v[130:131], 2, s[48:49]
	v_lshlrev_b32_e32 v130, 2, v16
	v_readlane_b32 s5, v253, 26
	v_mov_b32_e32 v8, 0x5000
	v_lshlrev_b32_e32 v1, 2, v1
	v_lshl_add_u64 v[6:7], s[4:5], 0, v[130:131]
	v_lshl_add_u32 v8, v14, 2, v8
	s_mov_b64 s[4:5], 0
	s_branch .LBB0_1067
